# P0 row loop: distance-2 cache-warming loads (row m+2N touched one row early so the real prefetch hits L2), b_f load hoisted
# baseline (speedup 1.0000x reference)
.LBB0_21:
	s_or_b64 exec, exec, s[60:61]
	s_add_u32 s4, s4, s30
	v_lshl_add_u64 v[40:41], v[40:41], 0, s[28:29]
	s_addc_u32 s5, s5, s31
	s_andn2_b64 vcc, exec, s[52:53]
	s_mov_b32 s26, s34
	s_cmp_eq_u32 s100, 0
	s_cbranch_scc1 .Lp0_w4
	s_waitcnt vmcnt(10)
	s_branch .Lp0_wd
.Lp0_w4:
	s_waitcnt vmcnt(4)
.Lp0_wd:
	v_mov_b32_e32 v30, v2
	v_mov_b32_e32 v31, v3
	v_mov_b32_e32 v32, v4
	v_mov_b32_e32 v33, v5
	v_mov_b32_e32 v26, v6
	v_mov_b32_e32 v27, v7
	v_mov_b32_e32 v28, v8
	v_mov_b32_e32 v29, v9
	v_mov_b32_e32 v22, v10
	v_mov_b32_e32 v23, v11
	v_mov_b32_e32 v24, v12
	v_mov_b32_e32 v25, v13
	v_mov_b32_e32 v18, v14
	s_waitcnt lgkmcnt(0)
	v_mov_b32_e32 v19, v15
	v_mov_b32_e32 v20, v16
	v_mov_b32_e32 v21, v17
	s_cbranch_vccz .LBB0_28
.LBB0_22:
	s_mov_b32 s100, 0
	s_add_i32 s34, s26, s20
	s_cmpk_gt_i32 s34, 0x3fff
	s_cselect_b64 s[52:53], -1, 0
	s_and_b64 vcc, exec, s[52:53]
	s_cbranch_vccnz .Lp0_nopf
	s_ashr_i32 s35, s34, 31
	s_lshl_b64 s[60:61], s[34:35], 12
	v_lshl_add_u64 v[14:15], v[36:37], 0, s[60:61]
	global_load_dwordx4 v[2:5], v[14:15], off nt
	global_load_dwordx4 v[6:9], v[14:15], off offset:1024 nt
	global_load_dwordx4 v[10:13], v[14:15], off offset:2048 nt
	s_nop 0
	global_load_dwordx4 v[14:17], v[14:15], off offset:3072 nt
	s_add_i32 s98, s34, s20
	s_cmpk_gt_i32 s98, 0x3fff
	s_cbranch_scc1 .Lp0_nodummy
	s_ashr_i32 s99, s98, 31
	s_lshl_b64 s[98:99], s[98:99], 12
	v_lshl_add_u64 v[254:255], v[36:37], 0, s[98:99]
	global_load_dwordx4 v[238:241], v[254:255], off
	global_load_dwordx4 v[242:245], v[254:255], off offset:1024
	global_load_dwordx4 v[246:249], v[254:255], off offset:2048
	s_nop 0
	global_load_dwordx4 v[250:253], v[254:255], off offset:3072
	s_mov_b32 s100, 1
.Lp0_nodummy:
.LBB0_24:
	s_waitcnt vmcnt(11)
	v_mul_f32_e32 v43, v31, v31
	v_mul_f32_e32 v55, v33, v33
	v_fmac_f32_e32 v43, v30, v30
	v_fmac_f32_e32 v55, v32, v32
	v_add_f32_e32 v43, v43, v55
	s_waitcnt vmcnt(10)
	v_mul_f32_e32 v55, v27, v27
	v_mul_f32_e32 v56, v29, v29
	v_fmac_f32_e32 v55, v26, v26
	v_fmac_f32_e32 v56, v28, v28
	v_add_f32_e32 v55, v55, v56
	v_add_f32_e32 v43, v43, v55
	s_waitcnt vmcnt(9)
	v_mul_f32_e32 v55, v23, v23
	v_mul_f32_e32 v56, v25, v25
	v_fmac_f32_e32 v55, v22, v22
	v_fmac_f32_e32 v56, v24, v24
	v_add_f32_e32 v55, v55, v56
	v_add_f32_e32 v43, v43, v55
	s_waitcnt vmcnt(8)
	v_mul_f32_e32 v55, v19, v19
	v_mul_f32_e32 v56, v21, v21
	v_fmac_f32_e32 v55, v18, v18
	v_fmac_f32_e32 v56, v20, v20
	v_add_f32_e32 v55, v55, v56
	v_add_f32_e32 v43, v43, v55
	ds_bpermute_b32 v55, v1, v43
	s_waitcnt lgkmcnt(0)
	v_add_f32_e32 v43, v43, v55
	ds_bpermute_b32 v55, v46, v43
	s_waitcnt lgkmcnt(0)
	v_add_f32_e32 v43, v43, v55
	ds_bpermute_b32 v55, v47, v43
	s_waitcnt lgkmcnt(0)
	v_add_f32_e32 v43, v43, v55
	ds_bpermute_b32 v55, v48, v43
	s_waitcnt lgkmcnt(0)
	v_add_f32_e32 v43, v43, v55
	ds_bpermute_b32 v55, v49, v43
	s_waitcnt lgkmcnt(0)
	v_add_f32_e32 v43, v43, v55
	ds_bpermute_b32 v55, v50, v43
	s_waitcnt lgkmcnt(0)
	v_add_f32_e32 v43, v43, v55
	s_and_saveexec_b64 s[60:61], s[6:7]
	s_cbranch_execz .LBB0_26
	s_add_u32 s88, s72, s4
	s_addc_u32 s89, s73, s5
	global_store_dword v35, v43, s[88:89]
